# grid barrier: all waiters poll the top-level arrive counter (the last leader's arrive is the release signal; no generation word, no per-XCD republish)
# baseline (speedup 1.0000x reference)
;     __device__ __forceinline__ const char* b(const Unit& u) const { return (const char*)Bt + (size_t)u.pn * 2 * hB() + (size_t)(u.pm >> gshift) * goff; }
;     __device__ __forceinline__ const char* b(const Unit& u) const { return (const char*)Bt + (size_t)((u.pn >> 4) * 4096 + (u.pn & 15) * 16) * 1024 * 2 + (size_t)(u.pm >> 1) * 512; }
;     __device__ __forceinline__ const char* b(const Unit& u) const { return (const char*)Bt + ((size_t)(((u.pm >> 4) * 1024 + u.pn * 256) * 16 + (u.pm & 15)) * 512) * 2; }
; __device__ __forceinline__ unsigned xb_ld(unsigned* p)              { return __hip_atomic_load(p, __ATOMIC_RELAXED, __HIP_MEMORY_SCOPE_AGENT); }
; __device__ __forceinline__ unsigned xb_add(unsigned* p, unsigned v) { return __hip_atomic_fetch_add(p, v, __ATOMIC_RELAXED, __HIP_MEMORY_SCOPE_AGENT); }
; #define XB_SPIN(cond, bar) do { unsigned _sp = 0; while (cond) { __builtin_amdgcn_s_sleep(1); \
;     if ((++_sp & 255u) == 0u) { if (xb_ld(&(bar)[XB_TMO])) break; if (_sp > XB_SPIN_CAP) { atomicAdd(&(bar)[XB_TMO], 1u); break; } } } } while (0)
; __device__ __forceinline__ void xcd_barrier(const XcdBarrier& b, const int wave) {
;     ...
;         const unsigned old = xb_add(&bar[XB_XSUB(b.x)], 1u);
;         const unsigned gen = old / nloc;
;         if (old + 1u == (gen + 1u) * nloc) {
;             __builtin_amdgcn_fence(__ATOMIC_RELEASE, "agent");
;             asm volatile("s_waitcnt vmcnt(0)" ::: "memory");
;             const unsigned og = xb_add(&bar[XB_TOP], 1u);
;             const unsigned tg = og / nx;
;             if (og + 1u == (tg + 1u) * nx) xb_add(&bar[XB_TOPGEN], 1u);
;             else XB_SPIN(xb_ld(&bar[XB_TOPGEN]) == tg, bar);
;             __builtin_amdgcn_fence(__ATOMIC_ACQUIRE, "agent");
;             xb_add(&bar[XB_XGEN(b.x)], 1u);
;             asm volatile("s_waitcnt vmcnt(0)" ::: "memory");
;         } else {
;             XB_SPIN(xb_ld(&bar[XB_XGEN(b.x)]) == gen, bar);
.LBB0_128:
	s_or_b64 exec, exec, s[10:11]
	s_waitcnt vmcnt(0) lgkmcnt(0)
	v_readfirstlane_b32 s8, v3
	v_add_u32_e32 v5, s8, v1
	v_add_u32_e32 v3, 1, v5
	v_mov_b32_e32 v1, 0
	v_mul_u32_u24_e32 v6, 1, v0
	v_mul_u32_u24_e32 v2, 1, v2
	v_cmp_ne_u32_e32 vcc, v3, v2
	s_and_saveexec_b64 s[8:9], vcc
	s_xor_b64 s[8:9], exec, s[8:9]
	s_cbranch_execz .LBB0_142
	s_waitcnt lgkmcnt(0)
	s_add_u32 s16, s94, 0x7400
	s_addc_u32 s17, s95, 0
	v_mov_b32_e32 v0, 0
	global_load_dword v0, v0, s[16:17] sc1
	s_waitcnt vmcnt(0)
	v_cmp_lt_u32_e32 vcc, v0, v6
	s_and_saveexec_b64 s[10:11], vcc
	s_cbranch_execz .LBB0_141
	s_add_u32 s12, s94, 0x4200
	s_addc_u32 s13, s95, 0
	s_mov_b32 s14, 1
	s_mov_b64 s[18:19], 0
	v_mov_b32_e32 v0, 0
	s_branch .LBB0_132

;     __device__ __forceinline__ const char* b(const Unit& u) const { return (const char*)Bt + (size_t)u.pn * 2 * hB() + (size_t)(u.pm >> gshift) * goff; }
;     __device__ __forceinline__ const char* b(const Unit& u) const { return (const char*)Bt + (size_t)((u.pn >> 4) * 4096 + (u.pn & 15) * 16) * 1024 * 2 + (size_t)(u.pm >> 1) * 512; }
;     __device__ __forceinline__ const char* b(const Unit& u) const { return (const char*)Bt + ((size_t)(((u.pm >> 4) * 1024 + u.pn * 256) * 16 + (u.pm & 15)) * 512) * 2; }
; __device__ __forceinline__ unsigned xb_ld(unsigned* p)              { return __hip_atomic_load(p, __ATOMIC_RELAXED, __HIP_MEMORY_SCOPE_AGENT); }
; #define XB_SPIN(cond, bar) do { unsigned _sp = 0; while (cond) { __builtin_amdgcn_s_sleep(1); \
;     if ((++_sp & 255u) == 0u) { if (xb_ld(&(bar)[XB_TMO])) break; if (_sp > XB_SPIN_CAP) { atomicAdd(&(bar)[XB_TMO], 1u); break; } } } } while (0)
; __device__ __forceinline__ void xcd_barrier(const XcdBarrier& b, const int wave) {
;     ...
;             XB_SPIN(xb_ld(&bar[XB_XGEN(b.x)]) == gen, bar);
.LBB0_134:
	global_load_dword v2, v0, s[16:17] sc1
	s_add_i32 s14, s14, 1
	s_mov_b64 s[26:27], -1
	s_waitcnt vmcnt(0)
	v_cmp_ge_u32_e32 vcc, v2, v6
	s_orn2_b64 s[22:23], vcc, exec
	s_branch .LBB0_131

; __device__ __forceinline__ unsigned xb_ld(unsigned* p)              { return __hip_atomic_load(p, __ATOMIC_RELAXED, __HIP_MEMORY_SCOPE_AGENT); }
; __device__ __forceinline__ unsigned xb_add(unsigned* p, unsigned v) { return __hip_atomic_fetch_add(p, v, __ATOMIC_RELAXED, __HIP_MEMORY_SCOPE_AGENT); }
; #define XB_SPIN(cond, bar) do { unsigned _sp = 0; while (cond) { __builtin_amdgcn_s_sleep(1); \
;     if ((++_sp & 255u) == 0u) { if (xb_ld(&(bar)[XB_TMO])) break; if (_sp > XB_SPIN_CAP) { atomicAdd(&(bar)[XB_TMO], 1u); break; } } } } while (0)
; __device__ __forceinline__ void xcd_barrier(const XcdBarrier& b, const int wave) {
;     ...
;             const unsigned og = xb_add(&bar[XB_TOP], 1u);
;             const unsigned tg = og / nx;
;             if (og + 1u == (tg + 1u) * nx) xb_add(&bar[XB_TOPGEN], 1u);
;             else XB_SPIN(xb_ld(&bar[XB_TOPGEN]) == tg, bar);
.LBB0_145:
	s_or_b64 exec, exec, s[10:11]
	s_waitcnt vmcnt(0)
	v_readfirstlane_b32 s8, v2
	s_add_u32 s10, s94, 0x7400
	s_addc_u32 s11, s95, 0
	s_mov_b64 s[12:13], 0
	v_add_u32_e32 v1, s8, v1
	v_add_u32_e32 v4, 1, v1
	v_mov_b32_e32 v2, 0
	v_mul_u32_u24_e32 v0, 1, v0
	v_mov_b32_e32 v5, v0
	v_cmp_ne_u32_e32 vcc, v4, v0
	v_mov_b64_e32 v[0:1], s[10:11]
	s_and_saveexec_b64 s[8:9], vcc
	s_cbranch_execz .LBB0_157
	v_mov_b32_e32 v0, 0
	global_load_dword v1, v0, s[10:11] sc1
	s_mov_b64 s[18:19], 0
	s_waitcnt vmcnt(0)
	v_cmp_lt_u32_e32 vcc, v1, v5
	s_and_saveexec_b64 s[16:17], vcc
	s_cbranch_execz .LBB0_156
	s_add_u32 s12, s94, 0x4200
	s_addc_u32 s13, s95, 0
	s_mov_b32 s14, 1
	s_branch .LBB0_149

; __device__ __forceinline__ unsigned xb_ld(unsigned* p)              { return __hip_atomic_load(p, __ATOMIC_RELAXED, __HIP_MEMORY_SCOPE_AGENT); }
; #define XB_SPIN(cond, bar) do { unsigned _sp = 0; while (cond) { __builtin_amdgcn_s_sleep(1); \
;     if ((++_sp & 255u) == 0u) { if (xb_ld(&(bar)[XB_TMO])) break; if (_sp > XB_SPIN_CAP) { atomicAdd(&(bar)[XB_TMO], 1u); break; } } } } while (0)
; __device__ __forceinline__ void xcd_barrier(const XcdBarrier& b, const int wave) {
;     ...
;             else XB_SPIN(xb_ld(&bar[XB_TOPGEN]) == tg, bar);
.LBB0_151:
	global_load_dword v1, v0, s[10:11] sc1
	s_add_i32 s14, s14, 1
	s_mov_b64 s[22:23], -1
	s_waitcnt vmcnt(0)
	v_cmp_ge_u32_e32 vcc, v1, v5
	s_orn2_b64 s[28:29], vcc, exec
	s_branch .LBB0_148

;     __device__ __forceinline__ const char* b(const Unit& u) const { return (const char*)Bt + (size_t)u.pn * 2 * hB() + (size_t)(u.pm >> gshift) * goff; }
;     __device__ __forceinline__ const char* b(const Unit& u) const { return (const char*)Bt + (size_t)((u.pn >> 4) * 4096 + (u.pn & 15) * 16) * 1024 * 2 + (size_t)(u.pm >> 1) * 512; }
;     __device__ __forceinline__ const char* b(const Unit& u) const { return (const char*)Bt + ((size_t)(((u.pm >> 4) * 1024 + u.pn * 256) * 16 + (u.pm & 15)) * 512) * 2; }
; __device__ __forceinline__ unsigned xb_ld(unsigned* p)              { return __hip_atomic_load(p, __ATOMIC_RELAXED, __HIP_MEMORY_SCOPE_AGENT); }
; __device__ __forceinline__ unsigned xb_add(unsigned* p, unsigned v) { return __hip_atomic_fetch_add(p, v, __ATOMIC_RELAXED, __HIP_MEMORY_SCOPE_AGENT); }
; #define XB_SPIN(cond, bar) do { unsigned _sp = 0; while (cond) { __builtin_amdgcn_s_sleep(1); \
;     if ((++_sp & 255u) == 0u) { if (xb_ld(&(bar)[XB_TMO])) break; if (_sp > XB_SPIN_CAP) { atomicAdd(&(bar)[XB_TMO], 1u); break; } } } } while (0)
; __device__ __forceinline__ void xcd_barrier(const XcdBarrier& b, const int wave) {
;     ...
;         const unsigned old = xb_add(&bar[XB_XSUB(b.x)], 1u);
;         const unsigned gen = old / nloc;
;         if (old + 1u == (gen + 1u) * nloc) {
;             __builtin_amdgcn_fence(__ATOMIC_RELEASE, "agent");
;             asm volatile("s_waitcnt vmcnt(0)" ::: "memory");
;             const unsigned og = xb_add(&bar[XB_TOP], 1u);
;             const unsigned tg = og / nx;
;             if (og + 1u == (tg + 1u) * nx) xb_add(&bar[XB_TOPGEN], 1u);
;             else XB_SPIN(xb_ld(&bar[XB_TOPGEN]) == tg, bar);
;             __builtin_amdgcn_fence(__ATOMIC_ACQUIRE, "agent");
;             xb_add(&bar[XB_XGEN(b.x)], 1u);
;             asm volatile("s_waitcnt vmcnt(0)" ::: "memory");
;         } else {
;             XB_SPIN(xb_ld(&bar[XB_XGEN(b.x)]) == gen, bar);
.LBB0_304:
	s_or_b64 exec, exec, s[8:9]
	s_waitcnt vmcnt(0) lgkmcnt(0)
	v_readfirstlane_b32 s6, v3
	v_add_u32_e32 v5, s6, v1
	v_add_u32_e32 v3, 1, v5
	v_mov_b32_e32 v1, 1
	v_mul_u32_u24_e32 v6, 2, v0
	v_mul_u32_u24_e32 v2, 2, v2
	v_cmp_ne_u32_e32 vcc, v3, v2
	s_and_saveexec_b64 s[6:7], vcc
	s_xor_b64 s[6:7], exec, s[6:7]
	s_cbranch_execz .LBB0_318
	s_waitcnt lgkmcnt(0)
	s_add_u32 s12, s94, 0x7400
	s_addc_u32 s13, s95, 0
	v_mov_b32_e32 v0, 0
	global_load_dword v0, v0, s[12:13] sc1
	s_waitcnt vmcnt(0)
	v_cmp_lt_u32_e32 vcc, v0, v6
	s_and_saveexec_b64 s[8:9], vcc
	s_cbranch_execz .LBB0_317
	s_add_u32 s10, s94, 0x4200
	s_addc_u32 s11, s95, 0
	s_mov_b32 s14, 1
	s_mov_b64 s[16:17], 0
	v_mov_b32_e32 v0, 0
	s_branch .LBB0_308

;     __device__ __forceinline__ const char* b(const Unit& u) const { return (const char*)Bt + (size_t)u.pn * 2 * hB() + (size_t)(u.pm >> gshift) * goff; }
;     __device__ __forceinline__ const char* b(const Unit& u) const { return (const char*)Bt + (size_t)((u.pn >> 4) * 4096 + (u.pn & 15) * 16) * 1024 * 2 + (size_t)(u.pm >> 1) * 512; }
;     __device__ __forceinline__ const char* b(const Unit& u) const { return (const char*)Bt + ((size_t)(((u.pm >> 4) * 1024 + u.pn * 256) * 16 + (u.pm & 15)) * 512) * 2; }
; __device__ __forceinline__ unsigned xb_ld(unsigned* p)              { return __hip_atomic_load(p, __ATOMIC_RELAXED, __HIP_MEMORY_SCOPE_AGENT); }
; #define XB_SPIN(cond, bar) do { unsigned _sp = 0; while (cond) { __builtin_amdgcn_s_sleep(1); \
;     if ((++_sp & 255u) == 0u) { if (xb_ld(&(bar)[XB_TMO])) break; if (_sp > XB_SPIN_CAP) { atomicAdd(&(bar)[XB_TMO], 1u); break; } } } } while (0)
; __device__ __forceinline__ void xcd_barrier(const XcdBarrier& b, const int wave) {
;     ...
;             XB_SPIN(xb_ld(&bar[XB_XGEN(b.x)]) == gen, bar);
.LBB0_310:
	global_load_dword v2, v0, s[12:13] sc1
	s_add_i32 s14, s14, 1
	s_mov_b64 s[22:23], -1
	s_waitcnt vmcnt(0)
	v_cmp_ge_u32_e32 vcc, v2, v6
	s_orn2_b64 s[20:21], vcc, exec
	s_branch .LBB0_307

; __device__ __forceinline__ unsigned xb_ld(unsigned* p)              { return __hip_atomic_load(p, __ATOMIC_RELAXED, __HIP_MEMORY_SCOPE_AGENT); }
; __device__ __forceinline__ unsigned xb_add(unsigned* p, unsigned v) { return __hip_atomic_fetch_add(p, v, __ATOMIC_RELAXED, __HIP_MEMORY_SCOPE_AGENT); }
; #define XB_SPIN(cond, bar) do { unsigned _sp = 0; while (cond) { __builtin_amdgcn_s_sleep(1); \
;     if ((++_sp & 255u) == 0u) { if (xb_ld(&(bar)[XB_TMO])) break; if (_sp > XB_SPIN_CAP) { atomicAdd(&(bar)[XB_TMO], 1u); break; } } } } while (0)
; __device__ __forceinline__ void xcd_barrier(const XcdBarrier& b, const int wave) {
;     ...
;             const unsigned og = xb_add(&bar[XB_TOP], 1u);
;             const unsigned tg = og / nx;
;             if (og + 1u == (tg + 1u) * nx) xb_add(&bar[XB_TOPGEN], 1u);
;             else XB_SPIN(xb_ld(&bar[XB_TOPGEN]) == tg, bar);
.LBB0_321:
	s_or_b64 exec, exec, s[8:9]
	s_waitcnt vmcnt(0)
	v_readfirstlane_b32 s6, v2
	s_add_u32 s8, s94, 0x7400
	s_addc_u32 s9, s95, 0
	s_mov_b64 s[10:11], 0
	v_add_u32_e32 v1, s6, v1
	v_add_u32_e32 v4, 1, v1
	v_mov_b32_e32 v2, 1
	v_mul_u32_u24_e32 v0, 2, v0
	v_mov_b32_e32 v5, v0
	v_cmp_ne_u32_e32 vcc, v4, v0
	v_mov_b64_e32 v[0:1], s[8:9]
	s_and_saveexec_b64 s[6:7], vcc
	s_cbranch_execz .LBB0_333
	v_mov_b32_e32 v0, 0
	global_load_dword v1, v0, s[8:9] sc1
	s_mov_b64 s[16:17], 0
	s_waitcnt vmcnt(0)
	v_cmp_lt_u32_e32 vcc, v1, v5
	s_and_saveexec_b64 s[12:13], vcc
	s_cbranch_execz .LBB0_332
	s_add_u32 s10, s94, 0x4200
	s_addc_u32 s11, s95, 0
	s_mov_b32 s14, 1
	s_branch .LBB0_325

; __device__ __forceinline__ unsigned xb_ld(unsigned* p)              { return __hip_atomic_load(p, __ATOMIC_RELAXED, __HIP_MEMORY_SCOPE_AGENT); }
; #define XB_SPIN(cond, bar) do { unsigned _sp = 0; while (cond) { __builtin_amdgcn_s_sleep(1); \
;     if ((++_sp & 255u) == 0u) { if (xb_ld(&(bar)[XB_TMO])) break; if (_sp > XB_SPIN_CAP) { atomicAdd(&(bar)[XB_TMO], 1u); break; } } } } while (0)
; __device__ __forceinline__ void xcd_barrier(const XcdBarrier& b, const int wave) {
;     ...
;             else XB_SPIN(xb_ld(&bar[XB_TOPGEN]) == tg, bar);
.LBB0_327:
	global_load_dword v1, v0, s[8:9] sc1
	s_add_i32 s14, s14, 1
	s_mov_b64 s[20:21], -1
	s_waitcnt vmcnt(0)
	v_cmp_ge_u32_e32 vcc, v1, v5
	s_orn2_b64 s[24:25], vcc, exec
	s_branch .LBB0_324

;     __device__ __forceinline__ const char* b(const Unit& u) const { return (const char*)Bt + (size_t)u.pn * 2 * hB() + (size_t)(u.pm >> gshift) * goff; }
;     __device__ __forceinline__ const char* b(const Unit& u) const { return (const char*)Bt + (size_t)((u.pn >> 4) * 4096 + (u.pn & 15) * 16) * 1024 * 2 + (size_t)(u.pm >> 1) * 512; }
;     __device__ __forceinline__ const char* b(const Unit& u) const { return (const char*)Bt + ((size_t)(((u.pm >> 4) * 1024 + u.pn * 256) * 16 + (u.pm & 15)) * 512) * 2; }
; __device__ __forceinline__ unsigned xb_ld(unsigned* p)              { return __hip_atomic_load(p, __ATOMIC_RELAXED, __HIP_MEMORY_SCOPE_AGENT); }
; __device__ __forceinline__ unsigned xb_add(unsigned* p, unsigned v) { return __hip_atomic_fetch_add(p, v, __ATOMIC_RELAXED, __HIP_MEMORY_SCOPE_AGENT); }
; #define XB_SPIN(cond, bar) do { unsigned _sp = 0; while (cond) { __builtin_amdgcn_s_sleep(1); \
;     if ((++_sp & 255u) == 0u) { if (xb_ld(&(bar)[XB_TMO])) break; if (_sp > XB_SPIN_CAP) { atomicAdd(&(bar)[XB_TMO], 1u); break; } } } } while (0)
; __device__ __forceinline__ void xcd_barrier(const XcdBarrier& b, const int wave) {
;     ...
;         const unsigned old = xb_add(&bar[XB_XSUB(b.x)], 1u);
;         const unsigned gen = old / nloc;
;         if (old + 1u == (gen + 1u) * nloc) {
;             __builtin_amdgcn_fence(__ATOMIC_RELEASE, "agent");
;             asm volatile("s_waitcnt vmcnt(0)" ::: "memory");
;             const unsigned og = xb_add(&bar[XB_TOP], 1u);
;             const unsigned tg = og / nx;
;             if (og + 1u == (tg + 1u) * nx) xb_add(&bar[XB_TOPGEN], 1u);
;             else XB_SPIN(xb_ld(&bar[XB_TOPGEN]) == tg, bar);
;             __builtin_amdgcn_fence(__ATOMIC_ACQUIRE, "agent");
;             xb_add(&bar[XB_XGEN(b.x)], 1u);
;             asm volatile("s_waitcnt vmcnt(0)" ::: "memory");
;         } else {
;             XB_SPIN(xb_ld(&bar[XB_XGEN(b.x)]) == gen, bar);
.LBB0_436:
	s_or_b64 exec, exec, s[10:11]
	s_waitcnt vmcnt(0) lgkmcnt(0)
	v_readfirstlane_b32 s8, v3
	v_add_u32_e32 v5, s8, v1
	v_add_u32_e32 v3, 1, v5
	v_mov_b32_e32 v1, 2
	v_mul_u32_u24_e32 v6, 3, v0
	v_mul_u32_u24_e32 v2, 3, v2
	v_cmp_ne_u32_e32 vcc, v3, v2
	s_and_saveexec_b64 s[8:9], vcc
	s_xor_b64 s[8:9], exec, s[8:9]
	s_cbranch_execz .LBB0_450
	s_waitcnt lgkmcnt(0)
	s_add_u32 s16, s94, 0x7400
	s_addc_u32 s17, s95, 0
	v_mov_b32_e32 v0, 0
	global_load_dword v0, v0, s[16:17] sc1
	s_waitcnt vmcnt(0)
	v_cmp_lt_u32_e32 vcc, v0, v6
	s_and_saveexec_b64 s[10:11], vcc
	s_cbranch_execz .LBB0_449
	s_add_u32 s12, s94, 0x4200
	s_addc_u32 s13, s95, 0
	s_mov_b32 s14, 1
	s_mov_b64 s[18:19], 0
	v_mov_b32_e32 v0, 0
	s_branch .LBB0_440

;     __device__ __forceinline__ const char* b(const Unit& u) const { return (const char*)Bt + (size_t)u.pn * 2 * hB() + (size_t)(u.pm >> gshift) * goff; }
;     __device__ __forceinline__ const char* b(const Unit& u) const { return (const char*)Bt + (size_t)((u.pn >> 4) * 4096 + (u.pn & 15) * 16) * 1024 * 2 + (size_t)(u.pm >> 1) * 512; }
;     __device__ __forceinline__ const char* b(const Unit& u) const { return (const char*)Bt + ((size_t)(((u.pm >> 4) * 1024 + u.pn * 256) * 16 + (u.pm & 15)) * 512) * 2; }
; __device__ __forceinline__ unsigned xb_ld(unsigned* p)              { return __hip_atomic_load(p, __ATOMIC_RELAXED, __HIP_MEMORY_SCOPE_AGENT); }
; #define XB_SPIN(cond, bar) do { unsigned _sp = 0; while (cond) { __builtin_amdgcn_s_sleep(1); \
;     if ((++_sp & 255u) == 0u) { if (xb_ld(&(bar)[XB_TMO])) break; if (_sp > XB_SPIN_CAP) { atomicAdd(&(bar)[XB_TMO], 1u); break; } } } } while (0)
; __device__ __forceinline__ void xcd_barrier(const XcdBarrier& b, const int wave) {
;     ...
;             XB_SPIN(xb_ld(&bar[XB_XGEN(b.x)]) == gen, bar);
.LBB0_442:
	global_load_dword v2, v0, s[16:17] sc1
	s_add_i32 s14, s14, 1
	s_mov_b64 s[24:25], -1
	s_waitcnt vmcnt(0)
	v_cmp_ge_u32_e32 vcc, v2, v6
	s_orn2_b64 s[22:23], vcc, exec
	s_branch .LBB0_439

; __device__ __forceinline__ unsigned xb_ld(unsigned* p)              { return __hip_atomic_load(p, __ATOMIC_RELAXED, __HIP_MEMORY_SCOPE_AGENT); }
; __device__ __forceinline__ unsigned xb_add(unsigned* p, unsigned v) { return __hip_atomic_fetch_add(p, v, __ATOMIC_RELAXED, __HIP_MEMORY_SCOPE_AGENT); }
; #define XB_SPIN(cond, bar) do { unsigned _sp = 0; while (cond) { __builtin_amdgcn_s_sleep(1); \
;     if ((++_sp & 255u) == 0u) { if (xb_ld(&(bar)[XB_TMO])) break; if (_sp > XB_SPIN_CAP) { atomicAdd(&(bar)[XB_TMO], 1u); break; } } } } while (0)
; __device__ __forceinline__ void xcd_barrier(const XcdBarrier& b, const int wave) {
;     ...
;             const unsigned og = xb_add(&bar[XB_TOP], 1u);
;             const unsigned tg = og / nx;
;             if (og + 1u == (tg + 1u) * nx) xb_add(&bar[XB_TOPGEN], 1u);
;             else XB_SPIN(xb_ld(&bar[XB_TOPGEN]) == tg, bar);
.LBB0_453:
	s_or_b64 exec, exec, s[10:11]
	s_waitcnt vmcnt(0)
	v_readfirstlane_b32 s8, v2
	s_add_u32 s10, s94, 0x7400
	s_addc_u32 s11, s95, 0
	s_mov_b64 s[12:13], 0
	v_add_u32_e32 v1, s8, v1
	v_add_u32_e32 v4, 1, v1
	v_mov_b32_e32 v2, 2
	v_mul_u32_u24_e32 v0, 3, v0
	v_mov_b32_e32 v5, v0
	v_cmp_ne_u32_e32 vcc, v4, v0
	v_mov_b64_e32 v[0:1], s[10:11]
	s_and_saveexec_b64 s[8:9], vcc
	s_cbranch_execz .LBB0_465
	v_mov_b32_e32 v0, 0
	global_load_dword v1, v0, s[10:11] sc1
	s_mov_b64 s[18:19], 0
	s_waitcnt vmcnt(0)
	v_cmp_lt_u32_e32 vcc, v1, v5
	s_and_saveexec_b64 s[16:17], vcc
	s_cbranch_execz .LBB0_464
	s_add_u32 s12, s94, 0x4200
	s_addc_u32 s13, s95, 0
	s_mov_b32 s14, 1
	s_branch .LBB0_457

; __device__ __forceinline__ unsigned xb_ld(unsigned* p)              { return __hip_atomic_load(p, __ATOMIC_RELAXED, __HIP_MEMORY_SCOPE_AGENT); }
; #define XB_SPIN(cond, bar) do { unsigned _sp = 0; while (cond) { __builtin_amdgcn_s_sleep(1); \
;     if ((++_sp & 255u) == 0u) { if (xb_ld(&(bar)[XB_TMO])) break; if (_sp > XB_SPIN_CAP) { atomicAdd(&(bar)[XB_TMO], 1u); break; } } } } while (0)
; __device__ __forceinline__ void xcd_barrier(const XcdBarrier& b, const int wave) {
;     ...
;             else XB_SPIN(xb_ld(&bar[XB_TOPGEN]) == tg, bar);
.LBB0_459:
	global_load_dword v1, v0, s[10:11] sc1
	s_add_i32 s14, s14, 1
	s_mov_b64 s[22:23], -1
	s_waitcnt vmcnt(0)
	v_cmp_ge_u32_e32 vcc, v1, v5
	s_orn2_b64 s[26:27], vcc, exec
	s_branch .LBB0_456

;     __device__ __forceinline__ const char* b(const Unit& u) const { return (const char*)Bt + (size_t)u.pn * 2 * hB() + (size_t)(u.pm >> gshift) * goff; }
;     __device__ __forceinline__ const char* b(const Unit& u) const { return (const char*)Bt + (size_t)((u.pn >> 4) * 4096 + (u.pn & 15) * 16) * 1024 * 2 + (size_t)(u.pm >> 1) * 512; }
;     __device__ __forceinline__ const char* b(const Unit& u) const { return (const char*)Bt + ((size_t)(((u.pm >> 4) * 1024 + u.pn * 256) * 16 + (u.pm & 15)) * 512) * 2; }
; __device__ __forceinline__ unsigned xb_ld(unsigned* p)              { return __hip_atomic_load(p, __ATOMIC_RELAXED, __HIP_MEMORY_SCOPE_AGENT); }
; __device__ __forceinline__ unsigned xb_add(unsigned* p, unsigned v) { return __hip_atomic_fetch_add(p, v, __ATOMIC_RELAXED, __HIP_MEMORY_SCOPE_AGENT); }
; #define XB_SPIN(cond, bar) do { unsigned _sp = 0; while (cond) { __builtin_amdgcn_s_sleep(1); \
;     if ((++_sp & 255u) == 0u) { if (xb_ld(&(bar)[XB_TMO])) break; if (_sp > XB_SPIN_CAP) { atomicAdd(&(bar)[XB_TMO], 1u); break; } } } } while (0)
; __device__ __forceinline__ void xcd_barrier(const XcdBarrier& b, const int wave) {
;     ...
;         const unsigned old = xb_add(&bar[XB_XSUB(b.x)], 1u);
;         const unsigned gen = old / nloc;
;         if (old + 1u == (gen + 1u) * nloc) {
;             __builtin_amdgcn_fence(__ATOMIC_RELEASE, "agent");
;             asm volatile("s_waitcnt vmcnt(0)" ::: "memory");
;             const unsigned og = xb_add(&bar[XB_TOP], 1u);
;             const unsigned tg = og / nx;
;             if (og + 1u == (tg + 1u) * nx) xb_add(&bar[XB_TOPGEN], 1u);
;             else XB_SPIN(xb_ld(&bar[XB_TOPGEN]) == tg, bar);
;             __builtin_amdgcn_fence(__ATOMIC_ACQUIRE, "agent");
;             xb_add(&bar[XB_XGEN(b.x)], 1u);
;             asm volatile("s_waitcnt vmcnt(0)" ::: "memory");
;         } else {
;             XB_SPIN(xb_ld(&bar[XB_XGEN(b.x)]) == gen, bar);
.LBB0_563:
	s_or_b64 exec, exec, s[8:9]
	s_waitcnt vmcnt(0) lgkmcnt(0)
	v_readfirstlane_b32 s6, v3
	v_add_u32_e32 v5, s6, v1
	v_add_u32_e32 v3, 1, v5
	v_mov_b32_e32 v1, 3
	v_mul_u32_u24_e32 v6, 4, v0
	v_mul_u32_u24_e32 v2, 4, v2
	v_cmp_ne_u32_e32 vcc, v3, v2
	s_and_saveexec_b64 s[6:7], vcc
	s_xor_b64 s[6:7], exec, s[6:7]
	s_cbranch_execz .LBB0_577
	s_waitcnt lgkmcnt(0)
	s_add_u32 s12, s94, 0x7400
	s_addc_u32 s13, s95, 0
	v_mov_b32_e32 v0, 0
	global_load_dword v0, v0, s[12:13] sc1
	s_waitcnt vmcnt(0)
	v_cmp_lt_u32_e32 vcc, v0, v6
	s_and_saveexec_b64 s[8:9], vcc
	s_cbranch_execz .LBB0_576
	s_add_u32 s10, s94, 0x4200
	s_addc_u32 s11, s95, 0
	s_mov_b32 s14, 1
	s_mov_b64 s[16:17], 0
	v_mov_b32_e32 v0, 0
	s_branch .LBB0_567

; __device__ __forceinline__ unsigned xb_ld(unsigned* p)              { return __hip_atomic_load(p, __ATOMIC_RELAXED, __HIP_MEMORY_SCOPE_AGENT); }
; __device__ __forceinline__ unsigned xb_add(unsigned* p, unsigned v) { return __hip_atomic_fetch_add(p, v, __ATOMIC_RELAXED, __HIP_MEMORY_SCOPE_AGENT); }
; #define XB_SPIN(cond, bar) do { unsigned _sp = 0; while (cond) { __builtin_amdgcn_s_sleep(1); \
;     if ((++_sp & 255u) == 0u) { if (xb_ld(&(bar)[XB_TMO])) break; if (_sp > XB_SPIN_CAP) { atomicAdd(&(bar)[XB_TMO], 1u); break; } } } } while (0)
; __device__ __forceinline__ void xcd_barrier(const XcdBarrier& b, const int wave) {
;     ...
;             const unsigned og = xb_add(&bar[XB_TOP], 1u);
;             const unsigned tg = og / nx;
;             if (og + 1u == (tg + 1u) * nx) xb_add(&bar[XB_TOPGEN], 1u);
;             else XB_SPIN(xb_ld(&bar[XB_TOPGEN]) == tg, bar);
.LBB0_580:
	s_or_b64 exec, exec, s[8:9]
	s_waitcnt vmcnt(0)
	v_readfirstlane_b32 s6, v2
	s_add_u32 s8, s94, 0x7400
	s_addc_u32 s9, s95, 0
	s_mov_b64 s[10:11], 0
	v_add_u32_e32 v1, s6, v1
	v_add_u32_e32 v4, 1, v1
	v_mov_b32_e32 v2, 3
	v_mul_u32_u24_e32 v0, 4, v0
	v_mov_b32_e32 v5, v0
	v_cmp_ne_u32_e32 vcc, v4, v0
	v_mov_b64_e32 v[0:1], s[8:9]
	s_and_saveexec_b64 s[6:7], vcc
	s_cbranch_execz .LBB0_592
	v_mov_b32_e32 v0, 0
	global_load_dword v1, v0, s[8:9] sc1
	s_mov_b64 s[16:17], 0
	s_waitcnt vmcnt(0)
	v_cmp_lt_u32_e32 vcc, v1, v5
	s_and_saveexec_b64 s[12:13], vcc
	s_cbranch_execz .LBB0_591
	s_add_u32 s10, s94, 0x4200
	s_addc_u32 s11, s95, 0
	s_mov_b32 s14, 1
	s_branch .LBB0_584

;     __device__ __forceinline__ const char* b(const Unit& u) const { return (const char*)Bt + (size_t)u.pn * 2 * hB() + (size_t)(u.pm >> gshift) * goff; }
;     __device__ __forceinline__ const char* b(const Unit& u) const { return (const char*)Bt + (size_t)((u.pn >> 4) * 4096 + (u.pn & 15) * 16) * 1024 * 2 + (size_t)(u.pm >> 1) * 512; }
;     __device__ __forceinline__ const char* b(const Unit& u) const { return (const char*)Bt + ((size_t)(((u.pm >> 4) * 1024 + u.pn * 256) * 16 + (u.pm & 15)) * 512) * 2; }
; __device__ __forceinline__ unsigned xb_ld(unsigned* p)              { return __hip_atomic_load(p, __ATOMIC_RELAXED, __HIP_MEMORY_SCOPE_AGENT); }
; __device__ __forceinline__ unsigned xb_add(unsigned* p, unsigned v) { return __hip_atomic_fetch_add(p, v, __ATOMIC_RELAXED, __HIP_MEMORY_SCOPE_AGENT); }
; #define XB_SPIN(cond, bar) do { unsigned _sp = 0; while (cond) { __builtin_amdgcn_s_sleep(1); \
;     if ((++_sp & 255u) == 0u) { if (xb_ld(&(bar)[XB_TMO])) break; if (_sp > XB_SPIN_CAP) { atomicAdd(&(bar)[XB_TMO], 1u); break; } } } } while (0)
; __device__ __forceinline__ void xcd_barrier(const XcdBarrier& b, const int wave) {
;     ...
;         const unsigned old = xb_add(&bar[XB_XSUB(b.x)], 1u);
;         const unsigned gen = old / nloc;
;         if (old + 1u == (gen + 1u) * nloc) {
;             __builtin_amdgcn_fence(__ATOMIC_RELEASE, "agent");
;             asm volatile("s_waitcnt vmcnt(0)" ::: "memory");
;             const unsigned og = xb_add(&bar[XB_TOP], 1u);
;             const unsigned tg = og / nx;
;             if (og + 1u == (tg + 1u) * nx) xb_add(&bar[XB_TOPGEN], 1u);
;             else XB_SPIN(xb_ld(&bar[XB_TOPGEN]) == tg, bar);
;             __builtin_amdgcn_fence(__ATOMIC_ACQUIRE, "agent");
;             xb_add(&bar[XB_XGEN(b.x)], 1u);
;             asm volatile("s_waitcnt vmcnt(0)" ::: "memory");
;         } else {
;             XB_SPIN(xb_ld(&bar[XB_XGEN(b.x)]) == gen, bar);
.LBB0_665:
	s_or_b64 exec, exec, s[8:9]
	s_waitcnt vmcnt(0) lgkmcnt(0)
	v_readfirstlane_b32 s6, v3
	v_add_u32_e32 v5, s6, v1
	v_add_u32_e32 v3, 1, v5
	v_mov_b32_e32 v1, 4
	v_mul_u32_u24_e32 v6, 5, v0
	v_mul_u32_u24_e32 v2, 5, v2
	v_cmp_ne_u32_e32 vcc, v3, v2
	s_and_saveexec_b64 s[6:7], vcc
	s_xor_b64 s[6:7], exec, s[6:7]
	s_cbranch_execz .LBB0_679
	s_waitcnt lgkmcnt(0)
	s_add_u32 s12, s94, 0x7400
	s_addc_u32 s13, s95, 0
	v_mov_b32_e32 v0, 0
	global_load_dword v0, v0, s[12:13] sc1
	s_waitcnt vmcnt(0)
	v_cmp_lt_u32_e32 vcc, v0, v6
	s_and_saveexec_b64 s[8:9], vcc
	s_cbranch_execz .LBB0_678
	s_add_u32 s10, s94, 0x4200
	s_addc_u32 s11, s95, 0
	s_mov_b32 s24, 1
	s_mov_b64 s[14:15], 0
	v_mov_b32_e32 v0, 0
	s_branch .LBB0_669

;     __device__ __forceinline__ const char* b(const Unit& u) const { return (const char*)Bt + (size_t)u.pn * 2 * hB() + (size_t)(u.pm >> gshift) * goff; }
;     __device__ __forceinline__ const char* b(const Unit& u) const { return (const char*)Bt + (size_t)((u.pn >> 4) * 4096 + (u.pn & 15) * 16) * 1024 * 2 + (size_t)(u.pm >> 1) * 512; }
;     __device__ __forceinline__ const char* b(const Unit& u) const { return (const char*)Bt + ((size_t)(((u.pm >> 4) * 1024 + u.pn * 256) * 16 + (u.pm & 15)) * 512) * 2; }
; __device__ __forceinline__ unsigned xb_ld(unsigned* p)              { return __hip_atomic_load(p, __ATOMIC_RELAXED, __HIP_MEMORY_SCOPE_AGENT); }
; #define XB_SPIN(cond, bar) do { unsigned _sp = 0; while (cond) { __builtin_amdgcn_s_sleep(1); \
;     if ((++_sp & 255u) == 0u) { if (xb_ld(&(bar)[XB_TMO])) break; if (_sp > XB_SPIN_CAP) { atomicAdd(&(bar)[XB_TMO], 1u); break; } } } } while (0)
; __device__ __forceinline__ void xcd_barrier(const XcdBarrier& b, const int wave) {
;     ...
;             XB_SPIN(xb_ld(&bar[XB_XGEN(b.x)]) == gen, bar);
.LBB0_671:
	global_load_dword v2, v0, s[12:13] sc1
	s_add_i32 s24, s24, 1
	s_mov_b64 s[20:21], -1
	s_waitcnt vmcnt(0)
	v_cmp_ge_u32_e32 vcc, v2, v6
	s_orn2_b64 s[18:19], vcc, exec
	s_branch .LBB0_668

; __device__ __forceinline__ unsigned xb_ld(unsigned* p)              { return __hip_atomic_load(p, __ATOMIC_RELAXED, __HIP_MEMORY_SCOPE_AGENT); }
; __device__ __forceinline__ unsigned xb_add(unsigned* p, unsigned v) { return __hip_atomic_fetch_add(p, v, __ATOMIC_RELAXED, __HIP_MEMORY_SCOPE_AGENT); }
; #define XB_SPIN(cond, bar) do { unsigned _sp = 0; while (cond) { __builtin_amdgcn_s_sleep(1); \
;     if ((++_sp & 255u) == 0u) { if (xb_ld(&(bar)[XB_TMO])) break; if (_sp > XB_SPIN_CAP) { atomicAdd(&(bar)[XB_TMO], 1u); break; } } } } while (0)
; __device__ __forceinline__ void xcd_barrier(const XcdBarrier& b, const int wave) {
;     ...
;             const unsigned og = xb_add(&bar[XB_TOP], 1u);
;             const unsigned tg = og / nx;
;             if (og + 1u == (tg + 1u) * nx) xb_add(&bar[XB_TOPGEN], 1u);
;             else XB_SPIN(xb_ld(&bar[XB_TOPGEN]) == tg, bar);
.LBB0_682:
	s_or_b64 exec, exec, s[8:9]
	s_waitcnt vmcnt(0)
	v_readfirstlane_b32 s6, v2
	s_add_u32 s8, s94, 0x7400
	s_addc_u32 s9, s95, 0
	s_mov_b64 s[10:11], 0
	v_add_u32_e32 v1, s6, v1
	v_add_u32_e32 v4, 1, v1
	v_mov_b32_e32 v2, 4
	v_mul_u32_u24_e32 v0, 5, v0
	v_mov_b32_e32 v5, v0
	v_cmp_ne_u32_e32 vcc, v4, v0
	v_mov_b64_e32 v[0:1], s[8:9]
	s_and_saveexec_b64 s[6:7], vcc
	s_cbranch_execz .LBB0_694
	v_mov_b32_e32 v0, 0
	global_load_dword v1, v0, s[8:9] sc1
	s_mov_b64 s[14:15], 0
	s_waitcnt vmcnt(0)
	v_cmp_lt_u32_e32 vcc, v1, v5
	s_and_saveexec_b64 s[12:13], vcc
	s_cbranch_execz .LBB0_693
	s_add_u32 s10, s94, 0x4200
	s_addc_u32 s11, s95, 0
	s_mov_b32 s24, 1
	s_branch .LBB0_686

; __device__ __forceinline__ unsigned xb_ld(unsigned* p)              { return __hip_atomic_load(p, __ATOMIC_RELAXED, __HIP_MEMORY_SCOPE_AGENT); }
; #define XB_SPIN(cond, bar) do { unsigned _sp = 0; while (cond) { __builtin_amdgcn_s_sleep(1); \
;     if ((++_sp & 255u) == 0u) { if (xb_ld(&(bar)[XB_TMO])) break; if (_sp > XB_SPIN_CAP) { atomicAdd(&(bar)[XB_TMO], 1u); break; } } } } while (0)
; __device__ __forceinline__ void xcd_barrier(const XcdBarrier& b, const int wave) {
;     ...
;             else XB_SPIN(xb_ld(&bar[XB_TOPGEN]) == tg, bar);
.LBB0_688:
	global_load_dword v1, v0, s[8:9] sc1
	s_add_i32 s24, s24, 1
	s_mov_b64 s[18:19], -1
	s_waitcnt vmcnt(0)
	v_cmp_ge_u32_e32 vcc, v1, v5
	s_orn2_b64 s[22:23], vcc, exec
	s_branch .LBB0_685

; __global__ void __launch_bounds__(NWAVES * 64, 2) mk_fwd(Args args) {
;     ...
;     const bool fuse7 = G >= (T / 2 / 256) * (DM / 256);
;     for (int half = 0; half < 2; ++half) {
;         const size_t roff = (size_t)half * (T / 2);
;         bf16_t* const ab = (fuse7 && half) ? (bf16_t*)(ws + WS_XB) : abuf;
;         {
;             pg8::AddrStd g{h1b + roff * DM, wup, 2048, 2048, 30, 0u}; pg8::StaticOrder S; S.init(T / 2, DFF, G, (int)blockIdx.x, WGM_U);
;             pg8::EpiB<2, 2, false> E{ab, DFF, ssq1 + roff, nullptr, 0, 0, 1.f};
;             pg8::gemm_phase<pg8::EpiB<2, 2, false>, pg8::StaticOrder, pg8::AddrStd, true>(lds, 2048, g, S, E, wave);
;         }
;         xcd_barrier(bar, wave);
;         if (fuse7) {
;             pg8::AddrStd g{ab, wd, DFF, DFF, 30, 0u}; pg8::StaticOrder S; S.init(T / 2, 2048, G, (int)blockIdx.x, WGM_D);
;             pg8::EpiResOut E{h1b + roff * DM, (unsigned long long*)(ws + WS_SSQX) + roff, out + roff * DM, g_fin, (unsigned*)(ws + WS_CTL) + CW_BAR + XB_TMO, 2048, 32u};
;             pg8::gemm_phase<pg8::EpiResOut, pg8::StaticOrder, pg8::AddrStd, true>(lds, DFF, g, S, E, wave);
.LBB0_700:
	v_writelane_b32 v254, s66, 36
	s_add_u32 s0, s94, 0x60000
	s_mov_b32 s70, -1
	v_writelane_b32 v254, s67, 37
	v_writelane_b32 v254, s0, 38
	s_addc_u32 s0, s95, 0
	s_cmpk_gt_i32 s3, 0xff
	v_writelane_b32 v254, s0, 39
	s_cselect_b64 s[0:1], -1, 0
	v_writelane_b32 v254, s0, 40
	s_cmpk_lt_i32 s3, 0x100
	v_mov_b32_e32 v193, 0
	v_writelane_b32 v254, s1, 41
	s_cselect_b64 s[0:1], -1, 0
	v_writelane_b32 v254, s0, 42
	s_ashr_i32 s51, s2, 31
	v_mov_b32_e32 v227, 0x358637bd
	v_writelane_b32 v254, s1, 43
	s_lshr_b32 s0, s51, 29
	s_add_i32 s0, s2, s0
	s_ashr_i32 s20, s0, 3
	s_and_b32 s0, s0, -8
	s_sub_i32 s0, s2, s0
	s_lshl_b32 s1, s0, 7
	v_readlane_b32 s4, v254, 16
	s_cmp_eq_u32 s4, 1
	v_readlane_b32 s4, v254, 14
	s_cselect_b64 s[24:25], -1, 0
	s_cmpk_lt_u32 s4, 0x100
	s_cselect_b64 s[82:83], -1, 0
	s_ashr_i32 s49, s3, 31
	s_add_u32 s84, s94, 0x4200
	s_addc_u32 s85, s95, 0
	s_add_u32 s44, s94, 0x4400
	s_addc_u32 s45, s95, 0
	s_add_u32 s46, s94, 0x4500
	s_addc_u32 s47, s95, 0
	s_add_u32 s52, s94, 0x4600
	s_addc_u32 s53, s95, 0
	s_add_u32 s54, s94, 0x4700
	s_addc_u32 s55, s95, 0
	s_add_u32 s28, s94, 0x4800
	s_addc_u32 s29, s95, 0
	s_add_u32 s96, s94, 0x4900
	s_addc_u32 s97, s95, 0
	s_add_u32 s60, s94, 0x4a00
	s_addc_u32 s61, s95, 0
	s_add_u32 s58, s94, 0x4b00
	s_addc_u32 s59, s95, 0
	s_add_u32 s4, s94, 0x4c00
	s_addc_u32 s5, s95, 0
	s_add_u32 s6, s94, 0x4d00
	s_addc_u32 s7, s95, 0
	s_add_u32 s8, s94, 0x4e00
	s_addc_u32 s9, s95, 0
	s_add_u32 s10, s94, 0x4f00
	s_addc_u32 s11, s95, 0
	s_add_u32 s12, s94, 0x5000
	s_addc_u32 s13, s95, 0
	s_add_u32 s14, s94, 0x5100
	s_addc_u32 s15, s95, 0
	s_add_u32 s16, s94, 0x5200
	s_addc_u32 s17, s95, 0
	s_add_u32 s18, s94, 0x5300
	s_addc_u32 s19, s95, 0
	v_readlane_b32 s21, v254, 6
	s_cmp_eq_u32 s21, 15
	s_cselect_b64 s[22:23], -1, 0
	v_writelane_b32 v254, s22, 44
	s_cmp_eq_u32 s21, 14
	v_mov_b32_e32 v228, 1
	v_writelane_b32 v254, s23, 45
	s_cselect_b64 s[22:23], -1, 0
	v_writelane_b32 v254, s22, 46
	s_cmp_eq_u32 s21, 13
	s_movk_i32 s71, 0x1fff
	v_writelane_b32 v254, s23, 47
	s_cselect_b64 s[22:23], -1, 0
	v_writelane_b32 v254, s22, 48
	s_cmp_eq_u32 s21, 12
	v_mov_b64_e32 v[194:195], 0x400
	v_writelane_b32 v254, s23, 49
	s_cselect_b64 s[22:23], -1, 0
	v_writelane_b32 v254, s22, 50
	s_cmp_eq_u32 s21, 11
	v_mov_b64_e32 v[196:197], 0x3ff
	v_writelane_b32 v254, s23, 51
	s_cselect_b64 s[22:23], -1, 0
	v_writelane_b32 v254, s22, 52
	s_cmp_eq_u32 s21, 10
	v_mov_b64_e32 v[198:199], 0x100
	v_writelane_b32 v254, s23, 53
	s_cselect_b64 s[22:23], -1, 0
	v_writelane_b32 v254, s22, 54
	s_cmp_eq_u32 s21, 9
	v_mov_b64_e32 v[200:201], 0xff
	v_writelane_b32 v254, s23, 55
	s_cselect_b64 s[22:23], -1, 0
	v_writelane_b32 v254, s22, 56
	s_cmp_eq_u32 s21, 8
	v_mbcnt_hi_u32_b32 v229, -1, v253
	v_writelane_b32 v254, s23, 57
	s_cselect_b64 s[22:23], -1, 0
	v_writelane_b32 v254, s22, 58
	s_cmp_eq_u32 s21, 7
	s_mov_b32 s72, 0x46800000
	v_writelane_b32 v254, s23, 59
	s_cselect_b64 s[22:23], -1, 0
	v_writelane_b32 v254, s22, 60
	s_cmp_eq_u32 s21, 6
	s_mov_b64 s[78:79], 0
	v_writelane_b32 v254, s23, 61
	s_cselect_b64 s[22:23], -1, 0
	v_writelane_b32 v254, s22, 62
	s_cmp_eq_u32 s21, 5
	s_waitcnt lgkmcnt(0)
	v_writelane_b32 v254, s23, 63
	s_cselect_b64 s[22:23], -1, 0
	v_writelane_b32 v255, s22, 0
	s_cmp_eq_u32 s21, 4
	s_barrier
; __global__ void __launch_bounds__(NWAVES * 64, 2) mk_fwd(Args args) {
;     ...
;     for (int half = 0; half < 2; ++half) {
;         const size_t roff = (size_t)half * (T / 2);
;         bf16_t* const ab = (fuse7 && half) ? (bf16_t*)(ws + WS_XB) : abuf;
;         {
;             pg8::AddrStd g{h1b + roff * DM, wup, 2048, 2048, 30, 0u}; pg8::StaticOrder S; S.init(T / 2, DFF, G, (int)blockIdx.x, WGM_U);
;             pg8::EpiB<2, 2, false> E{ab, DFF, ssq1 + roff, nullptr, 0, 0, 1.f};
;             pg8::gemm_phase<pg8::EpiB<2, 2, false>, pg8::StaticOrder, pg8::AddrStd, true>(lds, 2048, g, S, E, wave);
;         }
;         xcd_barrier(bar, wave);
;         if (fuse7) {
;             pg8::AddrStd g{ab, wd, DFF, DFF, 30, 0u}; pg8::StaticOrder S; S.init(T / 2, 2048, G, (int)blockIdx.x, WGM_D);
;             pg8::EpiResOut E{h1b + roff * DM, (unsigned long long*)(ws + WS_SSQX) + roff, out + roff * DM, g_fin, (unsigned*)(ws + WS_CTL) + CW_BAR + XB_TMO, 2048, 32u};
;             pg8::gemm_phase<pg8::EpiResOut, pg8::StaticOrder, pg8::AddrStd, true>(lds, DFF, g, S, E, wave);
	v_writelane_b32 v255, s23, 1
	s_cselect_b64 s[22:23], -1, 0
	v_writelane_b32 v255, s22, 2
	s_cmp_eq_u32 s21, 3
	s_nop 0
	v_writelane_b32 v255, s23, 3
	s_cselect_b64 s[22:23], -1, 0
	v_writelane_b32 v255, s22, 4
	s_cmp_eq_u32 s21, 2
	s_nop 0
	v_writelane_b32 v255, s23, 5
	s_cselect_b64 s[22:23], -1, 0
	v_writelane_b32 v255, s22, 6
	s_cmp_eq_u32 s21, 1
	s_nop 0
	v_writelane_b32 v255, s23, 7
	s_cselect_b64 s[22:23], -1, 0
	v_writelane_b32 v255, s22, 8
	s_cmp_eq_u32 s21, 0
	s_nop 0
	v_writelane_b32 v255, s23, 9
	s_cselect_b64 s[22:23], -1, 0
	s_lshl_b32 s21, s21, 8
	v_writelane_b32 v255, s22, 10
	s_add_u32 s21, s88, s21
	s_nop 0
	v_writelane_b32 v255, s23, 11
	s_addc_u32 s22, s89, 0
	s_add_u32 s26, s21, 0x1400
	s_addc_u32 s27, s22, 0
	v_writelane_b32 v255, s26, 12
	s_nop 1
	v_writelane_b32 v255, s27, 13
	s_add_u32 s26, s94, 0x7400
	s_addc_u32 s27, s95, 0
	s_add_u32 s22, s94, 0x7400
	s_addc_u32 s23, s95, 0
	v_writelane_b32 v255, s22, 14
	v_writelane_b32 v254, s26, 32
	s_nop 0
	v_writelane_b32 v255, s23, 15
	s_add_u32 s22, s94, 0x7400
	v_writelane_b32 v254, s27, 33
	s_addc_u32 s23, s95, 0
	v_writelane_b32 v254, s22, 14
	s_lshl_b32 s21, s0, 5
	s_nop 0
	v_writelane_b32 v254, s23, 15
	s_add_u32 s22, s94, 0x80000
	v_writelane_b32 v255, s22, 16
	s_addc_u32 s22, s95, 0
	v_writelane_b32 v255, s22, 17
	s_cmp_lt_i32 s0, 0
	s_mul_i32 s22, s0, 0x81
	s_cselect_b32 s1, s22, s1
	s_mul_i32 s0, s0, 33
	s_cselect_b32 s21, s0, s21
	s_add_i32 s0, s1, s20
	s_ashr_i32 s1, s0, 31
	s_lshr_b32 s1, s1, 25
	s_add_i32 s1, s0, s1
	s_and_b32 s22, s1, 0xff80
	s_sub_i32 s0, s0, s22
	s_bfe_i32 s22, s0, 0x80000
	s_bfe_u32 s22, s22, 0x2000d
	s_add_i32 s22, s0, s22
	s_and_b32 s23, s22, 0xfc
	s_sub_i32 s0, s0, s23
	s_ashr_i32 s1, s1, 7
	s_bfe_i32 s22, s22, 0x80000
	s_lshl_b32 s1, s1, 2
	s_sext_i32_i16 s22, s22
	s_sext_i32_i8 s0, s0
	s_add_i32 s26, s1, s0
	s_ashr_i32 s0, s22, 2
	v_writelane_b32 v255, s0, 18
	s_lshr_b32 s0, s22, 2
	s_mov_b32 s22, s26
	s_ashr_i32 s27, s26, 31
	s_bfe_i64 s[0:1], s[0:1], 0x100000
	v_writelane_b32 v255, s22, 19
	s_lshl_b64 s[0:1], s[0:1], 20
	v_writelane_b32 v254, s24, 26
	v_writelane_b32 v255, s23, 20
	s_lshl_b64 s[22:23], s[26:27], 20
	s_add_u32 s0, s64, s0
	v_writelane_b32 v255, s22, 21
	s_addc_u32 s1, s65, s1
	v_writelane_b32 v254, s25, 27
	v_writelane_b32 v255, s23, 22
	s_add_u32 s22, s0, 0x80000
	s_addc_u32 s23, s1, 0
	v_writelane_b32 v255, s22, 23
	v_cndmask_b32_e64 v226, 0, 1, s[24:25]
	s_nop 0
	v_writelane_b32 v255, s23, 24
	s_add_u32 s22, s0, 0x80080
	v_writelane_b32 v255, s0, 25
	s_addc_u32 s23, s1, 0
	s_nop 0
	v_writelane_b32 v255, s1, 26
	s_add_i32 s0, s21, s20
	s_ashr_i32 s1, s0, 31
	s_lshr_b32 s1, s1, 27
	s_add_i32 s1, s0, s1
	s_and_b32 s20, s1, 0xffe0
	s_sub_i32 s0, s0, s20
	s_bfe_i32 s20, s0, 0x80000
	s_bfe_u32 s20, s20, 0x2000d
	s_add_i32 s20, s0, s20
	s_and_b32 s21, s20, 0xfc
	s_sub_i32 s0, s0, s21
	s_ashr_i32 s1, s1, 5
	s_bfe_i32 s20, s20, 0x80000
	v_writelane_b32 v255, s22, 27
	s_lshl_b32 s1, s1, 2
	s_sext_i32_i16 s20, s20
	s_sext_i32_i8 s0, s0
	v_writelane_b32 v255, s23, 28
	s_add_i32 s22, s1, s0
	s_ashr_i32 s0, s20, 2
	v_writelane_b32 v255, s0, 29
	s_lshr_b32 s0, s20, 2
	s_mov_b32 s20, s22
	s_ashr_i32 s23, s22, 31
	s_bfe_i64 s[0:1], s[0:1], 0x100000
	v_writelane_b32 v255, s20, 30
	s_lshl_b64 s[0:1], s[0:1], 22
	s_nop 0
	v_writelane_b32 v255, s21, 31
	s_lshl_b64 s[20:21], s[22:23], 22
	s_add_u32 s0, s62, s0
	s_addc_u32 s1, s63, s1
	s_add_u32 s22, s0, 0x200000
	s_addc_u32 s23, s1, 0
	v_writelane_b32 v255, s22, 32
	s_nop 1
	v_writelane_b32 v255, s23, 33
	s_add_u32 s22, s68, s20
	v_writelane_b32 v255, s20, 34
	s_addc_u32 s23, s69, s21
	s_nop 0
	v_writelane_b32 v255, s21, 35
	s_add_u32 s20, s22, 0x200000
	v_writelane_b32 v255, s22, 36
	s_addc_u32 s21, s23, 0
	s_nop 0
	v_writelane_b32 v255, s23, 37
	v_writelane_b32 v255, s20, 38
	s_nop 1
	v_writelane_b32 v255, s21, 39
	s_add_u32 s20, s0, 0x200080
	v_writelane_b32 v255, s0, 40
	s_addc_u32 s21, s1, 0
	s_nop 0
	v_writelane_b32 v255, s1, 41
	v_writelane_b32 v255, s20, 42
	s_add_i32 s0, 0, 0x20160
	s_nop 0
	v_writelane_b32 v255, s21, 43
	v_writelane_b32 v255, s0, 44
	s_add_i32 s0, 0, 0x20164
	v_writelane_b32 v255, s0, 45
	v_writelane_b32 v255, s44, 46
	s_mov_b64 s[0:1], -1
	v_writelane_b32 v254, s0, 10
	v_writelane_b32 v255, s45, 47
	v_writelane_b32 v255, s46, 48
	v_writelane_b32 v254, s1, 11
	s_mov_b64 s[20:21], 0
	v_writelane_b32 v255, s47, 49
	v_readlane_b32 s95, v254, 18
	v_writelane_b32 v254, s74, 6
	v_writelane_b32 v255, s52, 50
	s_nop 0
	v_writelane_b32 v254, s75, 7
	v_writelane_b32 v255, s53, 51
	v_writelane_b32 v255, s54, 52
	v_writelane_b32 v254, s28, 16
	s_nop 0
	v_writelane_b32 v255, s55, 53
	v_writelane_b32 v254, s29, 17
	s_branch .LBB0_703

;     __device__ __forceinline__ const char* b(const Unit& u) const { return (const char*)Bt + (size_t)u.pn * 2 * hB() + (size_t)(u.pm >> gshift) * goff; }
;     __device__ __forceinline__ const char* b(const Unit& u) const { return (const char*)Bt + (size_t)((u.pn >> 4) * 4096 + (u.pn & 15) * 16) * 1024 * 2 + (size_t)(u.pm >> 1) * 512; }
;     __device__ __forceinline__ const char* b(const Unit& u) const { return (const char*)Bt + ((size_t)(((u.pm >> 4) * 1024 + u.pn * 256) * 16 + (u.pm & 15)) * 512) * 2; }
; __device__ __forceinline__ unsigned xb_ld(unsigned* p)              { return __hip_atomic_load(p, __ATOMIC_RELAXED, __HIP_MEMORY_SCOPE_AGENT); }
; __device__ __forceinline__ unsigned xb_add(unsigned* p, unsigned v) { return __hip_atomic_fetch_add(p, v, __ATOMIC_RELAXED, __HIP_MEMORY_SCOPE_AGENT); }
; #define XB_SPIN(cond, bar) do { unsigned _sp = 0; while (cond) { __builtin_amdgcn_s_sleep(1); \
;     if ((++_sp & 255u) == 0u) { if (xb_ld(&(bar)[XB_TMO])) break; if (_sp > XB_SPIN_CAP) { atomicAdd(&(bar)[XB_TMO], 1u); break; } } } } while (0)
; __device__ __forceinline__ void xcd_barrier(const XcdBarrier& b, const int wave) {
;     ...
;         const unsigned old = xb_add(&bar[XB_XSUB(b.x)], 1u);
;         const unsigned gen = old / nloc;
;         if (old + 1u == (gen + 1u) * nloc) {
;             __builtin_amdgcn_fence(__ATOMIC_RELEASE, "agent");
;             asm volatile("s_waitcnt vmcnt(0)" ::: "memory");
;             const unsigned og = xb_add(&bar[XB_TOP], 1u);
;             const unsigned tg = og / nx;
;             if (og + 1u == (tg + 1u) * nx) xb_add(&bar[XB_TOPGEN], 1u);
;             else XB_SPIN(xb_ld(&bar[XB_TOPGEN]) == tg, bar);
;             __builtin_amdgcn_fence(__ATOMIC_ACQUIRE, "agent");
;             xb_add(&bar[XB_XGEN(b.x)], 1u);
;             asm volatile("s_waitcnt vmcnt(0)" ::: "memory");
;         } else {
;             XB_SPIN(xb_ld(&bar[XB_XGEN(b.x)]) == gen, bar);
.LBB0_742:
	s_or_b64 exec, exec, s[22:23]
	s_waitcnt vmcnt(0) lgkmcnt(0)
	v_readfirstlane_b32 s0, v3
	v_add_u32_e32 v5, s0, v1
	v_add_u32_e32 v3, 1, v5
	v_mul_u32_u24_e32 v4, 6, v2
	v_mul_u32_u24_e32 v6, 6, v0
	v_cmp_ge_u32_e32 vcc, v5, v4
	s_nop 1
	v_cndmask_b32_e64 v1, 5, 6, vcc
	v_cndmask_b32_e64 v2, 0, v2, vcc
	v_cndmask_b32_e64 v7, 0, v0, vcc
	v_add_u32_e32 v2, v4, v2
	v_add_u32_e32 v6, v6, v7
	v_cmp_ne_u32_e32 vcc, v3, v2
	s_and_saveexec_b64 s[0:1], vcc
	s_xor_b64 s[22:23], exec, s[0:1]
	s_cbranch_execz .LBB0_756
	v_readlane_b32 s0, v254, 32
	v_readlane_b32 s1, v254, 33
	s_waitcnt lgkmcnt(0)
	s_nop 3
	global_load_dword v0, v193, s[0:1] sc1
	s_waitcnt vmcnt(0)
	v_cmp_lt_u32_e32 vcc, v0, v6
	s_and_saveexec_b64 s[24:25], vcc
	s_cbranch_execz .LBB0_755
	s_mov_b32 s0, 1
	s_mov_b64 s[26:27], 0
	s_branch .LBB0_746

;     __device__ __forceinline__ const char* b(const Unit& u) const { return (const char*)Bt + (size_t)u.pn * 2 * hB() + (size_t)(u.pm >> gshift) * goff; }
;     __device__ __forceinline__ const char* b(const Unit& u) const { return (const char*)Bt + (size_t)((u.pn >> 4) * 4096 + (u.pn & 15) * 16) * 1024 * 2 + (size_t)(u.pm >> 1) * 512; }
;     __device__ __forceinline__ const char* b(const Unit& u) const { return (const char*)Bt + ((size_t)(((u.pm >> 4) * 1024 + u.pn * 256) * 16 + (u.pm & 15)) * 512) * 2; }
; __device__ __forceinline__ unsigned xb_ld(unsigned* p)              { return __hip_atomic_load(p, __ATOMIC_RELAXED, __HIP_MEMORY_SCOPE_AGENT); }
; #define XB_SPIN(cond, bar) do { unsigned _sp = 0; while (cond) { __builtin_amdgcn_s_sleep(1); \
;     if ((++_sp & 255u) == 0u) { if (xb_ld(&(bar)[XB_TMO])) break; if (_sp > XB_SPIN_CAP) { atomicAdd(&(bar)[XB_TMO], 1u); break; } } } } while (0)
; __device__ __forceinline__ void xcd_barrier(const XcdBarrier& b, const int wave) {
;     ...
;             XB_SPIN(xb_ld(&bar[XB_XGEN(b.x)]) == gen, bar);
.LBB0_748:
	v_readlane_b32 s34, v254, 32
	v_readlane_b32 s35, v254, 33
	s_add_i32 s0, s0, 1
	s_mov_b64 s[38:39], -1
	s_nop 2
	global_load_dword v0, v193, s[34:35] sc1
	s_waitcnt vmcnt(0)
	v_cmp_ge_u32_e32 vcc, v0, v6
	s_orn2_b64 s[36:37], vcc, exec
	s_branch .LBB0_745

; __device__ __forceinline__ unsigned xb_ld(unsigned* p)              { return __hip_atomic_load(p, __ATOMIC_RELAXED, __HIP_MEMORY_SCOPE_AGENT); }
; __device__ __forceinline__ unsigned xb_add(unsigned* p, unsigned v) { return __hip_atomic_fetch_add(p, v, __ATOMIC_RELAXED, __HIP_MEMORY_SCOPE_AGENT); }
; #define XB_SPIN(cond, bar) do { unsigned _sp = 0; while (cond) { __builtin_amdgcn_s_sleep(1); \
;     if ((++_sp & 255u) == 0u) { if (xb_ld(&(bar)[XB_TMO])) break; if (_sp > XB_SPIN_CAP) { atomicAdd(&(bar)[XB_TMO], 1u); break; } } } } while (0)
; __device__ __forceinline__ void xcd_barrier(const XcdBarrier& b, const int wave) {
;     ...
;             const unsigned og = xb_add(&bar[XB_TOP], 1u);
;             const unsigned tg = og / nx;
;             if (og + 1u == (tg + 1u) * nx) xb_add(&bar[XB_TOPGEN], 1u);
;             else XB_SPIN(xb_ld(&bar[XB_TOPGEN]) == tg, bar);
.LBB0_759:
	s_or_b64 exec, exec, s[24:25]
	s_waitcnt vmcnt(0)
	v_readfirstlane_b32 s0, v2
	v_add_u32_e32 v1, s0, v1
	v_readlane_b32 s0, v254, 14
	v_readlane_b32 s1, v254, 15
	s_mov_b64 s[24:25], 0
	v_mul_u32_u24_e32 v4, 6, v0
	v_cmp_ge_u32_e32 vcc, v1, v4
	s_nop 1
	v_cndmask_b32_e64 v2, 5, 6, vcc
	v_cndmask_b32_e64 v0, 0, v0, vcc
	v_add_u32_e32 v0, v4, v0
	v_mov_b32_e32 v5, v0
	v_add_u32_e32 v1, 1, v1
	v_cmp_ne_u32_e32 vcc, v1, v0
	v_mov_b64_e32 v[0:1], s[0:1]
	s_and_saveexec_b64 s[22:23], vcc
	s_cbranch_execz .LBB0_771
	v_readlane_b32 s0, v254, 14
	v_readlane_b32 s1, v254, 15
	s_mov_b64 s[26:27], 0
	s_nop 3
	global_load_dword v0, v193, s[0:1] sc1
	s_waitcnt vmcnt(0)
	v_cmp_lt_u32_e32 vcc, v0, v5
	s_and_saveexec_b64 s[24:25], vcc
	s_cbranch_execz .LBB0_770
	s_mov_b32 s0, 1
	s_branch .LBB0_763

; __device__ __forceinline__ unsigned xb_ld(unsigned* p)              { return __hip_atomic_load(p, __ATOMIC_RELAXED, __HIP_MEMORY_SCOPE_AGENT); }
; #define XB_SPIN(cond, bar) do { unsigned _sp = 0; while (cond) { __builtin_amdgcn_s_sleep(1); \
;     if ((++_sp & 255u) == 0u) { if (xb_ld(&(bar)[XB_TMO])) break; if (_sp > XB_SPIN_CAP) { atomicAdd(&(bar)[XB_TMO], 1u); break; } } } } while (0)
; __device__ __forceinline__ void xcd_barrier(const XcdBarrier& b, const int wave) {
;     ...
;             else XB_SPIN(xb_ld(&bar[XB_TOPGEN]) == tg, bar);
.LBB0_765:
	v_readlane_b32 s34, v254, 14
	v_readlane_b32 s35, v254, 15
	s_add_i32 s0, s0, 1
	s_mov_b64 s[38:39], -1
	s_nop 2
	global_load_dword v0, v193, s[34:35] sc1
	s_waitcnt vmcnt(0)
	v_cmp_ge_u32_e32 vcc, v0, v5
	s_orn2_b64 s[36:37], vcc, exec
	s_branch .LBB0_762
